# in-proj GEMM K-loop: 4 of the 6 LDS-DMA stages of each SP2 load segment moved into the following MFMA segment (interleaved every 8 MFMAs), SP2 waits vmcnt(8)->vmcnt(4)
# baseline (speedup 1.0000x reference)
; #define PG8_STAGE(bufoff, gbase, voff) do { _Pragma("unroll") for (int _i = 0; _i < 2; ++_i) \
;         __builtin_amdgcn_global_load_lds((const unsigned*)((const char*)(gbase) + (voff)[_i]), (PG8_LAS unsigned*)(lds + (bufoff) + ldsw + _i * 8192), 16, 0, 0); } while (0)
; #define PG8_LDA(dst, b, h) do { _Pragma("unroll") for (int m = 0; m < 4; ++m) _Pragma("unroll") for (int k = 0; k < 2; ++k) dst[m][k] = *(const PG8_LAS bf16x8*)(lds + PG8_SA(b, h) + aoff + m * 2048 + k * 1024); } while (0)
; #define PG8_LDB(dst, b, h) do { _Pragma("unroll") for (int n = 0; n < 2; ++n) _Pragma("unroll") for (int k = 0; k < 2; ++k) dst[n][k] = *(const PG8_LAS bf16x8*)(lds + PG8_SB(b, h) + boff + n * 2048 + k * 1024); } while (0)
; #define PG8_MMA(ai, bj, At, Bt) do { __builtin_amdgcn_s_setprio(1); _Pragma("unroll") for (int m = 0; m < 4; ++m) _Pragma("unroll") for (int n = 0; n < 2; ++n) _Pragma("unroll") for (int k = 0; k < 2; ++k) \
;         acc[ai][bj][m][n] = __builtin_amdgcn_mfma_f32_16x16x32_bf16(Bt[n][k], At[m][k], acc[ai][bj][m][n], 0, 0, 0); __builtin_amdgcn_s_setprio(0); } while (0)
; #define PG8_WAIT_V(n) asm volatile("s_waitcnt vmcnt(" #n ")" ::: "memory")
; #define PG8_WAIT_L(n) asm volatile("s_waitcnt lgkmcnt(" #n ")" ::: "memory")
; #define PG8_BAR __builtin_amdgcn_s_barrier()
; #define PG8_SCHED __builtin_amdgcn_sched_barrier(0)
; template <class Epi, class Sched, bool ALIGN_EPI = false, bool SP2 = false>
; __device__ __forceinline__ void gemm_phase(PG8_LAS unsigned char* lds, const Gemm g, const Sched& S, const Epi& E) {
;     ...
;             PG8_LDB(B0, 0, 0); PG8_LDB(B1, 0, 1); PG8_SCHED; PG8_LDA(At, 0, 0); PG8_STAGE(PG8_SA(1, 1), a1 + hstep, voffA);
;             PG8_WAIT_V(8); PG8_WAIT_L(0); PG8_BAR; PG8_MMA(0, 0, At, B0); PG8_MMA(0, 1, At, B1); PG8_BAR; PG8_SCHED;
;             PG8_LDA(At, 0, 1); PG8_STAGE(PG8_SB(0, 0), b2, voffB); PG8_STAGE(PG8_SB(0, 1), b2 + hstep, voffB); PG8_STAGE(PG8_SA(0, 0), a2, voffA);
;             PG8_WAIT_V(8); PG8_WAIT_L(0); PG8_BAR; PG8_MMA(1, 0, At, B0); PG8_MMA(1, 1, At, B1); PG8_BAR; PG8_SCHED;
.LBB0_411:
	ds_read_b128 v[130:133], v218
	ds_read_b128 v[134:137], v218 offset:1024
	ds_read_b128 v[138:141], v218 offset:2048
	ds_read_b128 v[142:145], v218 offset:3072
	ds_read_b128 v[146:149], v219
	ds_read_b128 v[150:153], v219 offset:1024
	ds_read_b128 v[154:157], v219 offset:2048
	ds_read_b128 v[158:161], v219 offset:3072
	s_add_u32 s6, s4, 0xfffc0080
	s_addc_u32 s7, s5, -1
	s_cmp_eq_u32 s37, 12
	s_cselect_b32 s45, s0, s7
	s_cselect_b32 s44, s1, s6
	s_cselect_b32 s7, s9, s35
	s_cselect_b32 s6, s12, s33
	v_lshl_add_u64 v[226:227], s[4:5], 0, v[188:189]
	s_add_i32 m0, s51, 0xc000
	s_waitcnt vmcnt(0)
	ds_read_b128 v[162:165], v220
	ds_read_b128 v[166:169], v220 offset:1024
	ds_read_b128 v[170:173], v220 offset:2048
	ds_read_b128 v[196:199], v220 offset:3072
	ds_read_b128 v[200:203], v220 offset:4096
	ds_read_b128 v[204:207], v220 offset:5120
	ds_read_b128 v[208:211], v220 offset:6144
	ds_read_b128 v[212:215], v220 offset:7168
	global_load_lds_dwordx4 v[226:227], off
	v_lshl_add_u64 v[226:227], s[4:5], 0, v[190:191]
	s_add_i32 m0, s51, 0xe000
	s_nop 0
	global_load_lds_dwordx4 v[226:227], off
	s_waitcnt vmcnt(8)
	s_waitcnt lgkmcnt(0)
	s_barrier
	s_setprio 1
	s_waitcnt lgkmcnt(0)
	v_mfma_f32_16x16x32_bf16 v[126:129], v[130:133], v[162:165], v[126:129]
	v_mfma_f32_16x16x32_bf16 v[122:125], v[138:141], v[162:165], v[122:125]
	v_mfma_f32_16x16x32_bf16 v[110:113], v[130:133], v[170:173], v[110:113]
	v_mfma_f32_16x16x32_bf16 v[106:109], v[138:141], v[170:173], v[106:109]
	v_mfma_f32_16x16x32_bf16 v[94:97], v[130:133], v[200:203], v[94:97]
	v_mfma_f32_16x16x32_bf16 v[90:93], v[138:141], v[200:203], v[90:93]
	v_mfma_f32_16x16x32_bf16 v[78:81], v[130:133], v[208:211], v[78:81]
	v_mfma_f32_16x16x32_bf16 v[74:77], v[138:141], v[208:211], v[74:77]
	v_mfma_f32_16x16x32_bf16 v[126:129], v[134:137], v[166:169], v[126:129]
	v_mfma_f32_16x16x32_bf16 v[122:125], v[142:145], v[166:169], v[122:125]
	v_mfma_f32_16x16x32_bf16 v[110:113], v[134:137], v[196:199], v[110:113]
	v_mfma_f32_16x16x32_bf16 v[106:109], v[142:145], v[196:199], v[106:109]
	v_mfma_f32_16x16x32_bf16 v[94:97], v[134:137], v[204:207], v[94:97]
	v_mfma_f32_16x16x32_bf16 v[90:93], v[142:145], v[204:207], v[90:93]
	v_mfma_f32_16x16x32_bf16 v[78:81], v[134:137], v[212:215], v[78:81]
	v_mfma_f32_16x16x32_bf16 v[74:77], v[142:145], v[212:215], v[74:77]
	s_setprio 0
	s_setprio 1
	v_mfma_f32_16x16x32_bf16 v[118:121], v[146:149], v[162:165], v[118:121]
	v_mfma_f32_16x16x32_bf16 v[114:117], v[154:157], v[162:165], v[114:117]
	v_mfma_f32_16x16x32_bf16 v[102:105], v[146:149], v[170:173], v[102:105]
	v_mfma_f32_16x16x32_bf16 v[98:101], v[154:157], v[170:173], v[98:101]
	v_mfma_f32_16x16x32_bf16 v[86:89], v[146:149], v[200:203], v[86:89]
	v_mfma_f32_16x16x32_bf16 v[82:85], v[154:157], v[200:203], v[82:85]
	v_mfma_f32_16x16x32_bf16 v[70:73], v[146:149], v[208:211], v[70:73]
	v_mfma_f32_16x16x32_bf16 v[66:69], v[154:157], v[208:211], v[66:69]
	v_mfma_f32_16x16x32_bf16 v[118:121], v[150:153], v[166:169], v[118:121]
	v_mfma_f32_16x16x32_bf16 v[114:117], v[158:161], v[166:169], v[114:117]
	v_mfma_f32_16x16x32_bf16 v[102:105], v[150:153], v[196:199], v[102:105]
	v_mfma_f32_16x16x32_bf16 v[98:101], v[158:161], v[196:199], v[98:101]
	v_mfma_f32_16x16x32_bf16 v[86:89], v[150:153], v[204:207], v[86:89]
	v_mfma_f32_16x16x32_bf16 v[82:85], v[158:161], v[204:207], v[82:85]
	v_mfma_f32_16x16x32_bf16 v[70:73], v[150:153], v[212:215], v[70:73]
	v_mfma_f32_16x16x32_bf16 v[66:69], v[158:161], v[212:215], v[66:69]
	s_setprio 0
	s_barrier
	s_add_i32 s43, s86, s50
	v_lshl_add_u64 v[226:227], s[6:7], 0, v[178:179]
	s_mov_b32 m0, s43
	ds_read_b128 v[162:165], v220 offset:16384
	ds_read_b128 v[166:169], v220 offset:17408
	ds_read_b128 v[170:173], v220 offset:18432
	ds_read_b128 v[196:199], v220 offset:19456
	ds_read_b128 v[200:203], v220 offset:20480
	ds_read_b128 v[204:207], v220 offset:21504
	ds_read_b128 v[208:211], v220 offset:22528
	ds_read_b128 v[212:215], v220 offset:23552
	global_load_lds_dwordx4 v[226:227], off
	s_add_i32 m0, s43, 0x2000
	s_add_u32 s46, s6, 0x40000
	v_lshl_add_u64 v[228:229], s[6:7], 0, v[182:183]
	s_addc_u32 s47, s7, 0
	s_add_i32 s43, s87, s50
	global_load_lds_dwordx4 v[228:229], off
	s_waitcnt vmcnt(4)
	s_waitcnt lgkmcnt(0)
	s_barrier
	s_setprio 1
	s_waitcnt lgkmcnt(0)
	v_mfma_f32_16x16x32_bf16 v[62:65], v[130:133], v[162:165], v[62:65]
	v_mfma_f32_16x16x32_bf16 v[58:61], v[138:141], v[162:165], v[58:61]
	v_mfma_f32_16x16x32_bf16 v[46:49], v[130:133], v[170:173], v[46:49]
	v_mfma_f32_16x16x32_bf16 v[42:45], v[138:141], v[170:173], v[42:45]
	v_lshl_add_u64 v[230:231], s[46:47], 0, v[178:179]
	s_mov_b32 m0, s43
	v_lshl_add_u64 v[232:233], s[44:45], 0, v[180:181]
	global_load_lds_dwordx4 v[230:231], off
	v_mfma_f32_16x16x32_bf16 v[30:33], v[130:133], v[200:203], v[30:33]
	v_mfma_f32_16x16x32_bf16 v[26:29], v[138:141], v[200:203], v[26:29]
	v_mfma_f32_16x16x32_bf16 v[14:17], v[130:133], v[208:211], v[14:17]
	v_mfma_f32_16x16x32_bf16 v[10:13], v[138:141], v[208:211], v[10:13]
	v_mfma_f32_16x16x32_bf16 v[62:65], v[134:137], v[166:169], v[62:65]
	v_mfma_f32_16x16x32_bf16 v[58:61], v[142:145], v[166:169], v[58:61]
	v_mfma_f32_16x16x32_bf16 v[46:49], v[134:137], v[196:199], v[46:49]
	v_mfma_f32_16x16x32_bf16 v[42:45], v[142:145], v[196:199], v[42:45]
	v_lshl_add_u64 v[230:231], s[46:47], 0, v[182:183]
	s_add_i32 m0, s43, 0x2000
	s_nop 0
	global_load_lds_dwordx4 v[230:231], off
	v_mfma_f32_16x16x32_bf16 v[30:33], v[134:137], v[204:207], v[30:33]
	v_mfma_f32_16x16x32_bf16 v[26:29], v[142:145], v[204:207], v[26:29]
	v_mfma_f32_16x16x32_bf16 v[14:17], v[134:137], v[212:215], v[14:17]
	v_mfma_f32_16x16x32_bf16 v[10:13], v[142:145], v[212:215], v[10:13]
	s_setprio 0
	s_setprio 1
	v_mfma_f32_16x16x32_bf16 v[54:57], v[146:149], v[162:165], v[54:57]
	v_mfma_f32_16x16x32_bf16 v[50:53], v[154:157], v[162:165], v[50:53]
	v_mfma_f32_16x16x32_bf16 v[38:41], v[146:149], v[170:173], v[38:41]
	v_mfma_f32_16x16x32_bf16 v[34:37], v[154:157], v[170:173], v[34:37]
	v_lshl_add_u64 v[230:231], s[44:45], 0, v[176:177]
	s_mov_b32 m0, s51
	s_nop 0
	global_load_lds_dwordx4 v[230:231], off
	v_mfma_f32_16x16x32_bf16 v[22:25], v[146:149], v[200:203], v[22:25]
	v_mfma_f32_16x16x32_bf16 v[18:21], v[154:157], v[200:203], v[18:21]
	v_mfma_f32_16x16x32_bf16 v[6:9], v[146:149], v[208:211], v[6:9]
	v_mfma_f32_16x16x32_bf16 v[2:5], v[154:157], v[208:211], v[2:5]
	v_mfma_f32_16x16x32_bf16 v[54:57], v[150:153], v[166:169], v[54:57]
	v_mfma_f32_16x16x32_bf16 v[50:53], v[158:161], v[166:169], v[50:53]
	v_mfma_f32_16x16x32_bf16 v[38:41], v[150:153], v[196:199], v[38:41]
	v_mfma_f32_16x16x32_bf16 v[34:37], v[158:161], v[196:199], v[34:37]
	s_mov_b32 m0, s52
	s_nop 0
	global_load_lds_dwordx4 v[232:233], off
	v_mfma_f32_16x16x32_bf16 v[22:25], v[150:153], v[204:207], v[22:25]
	v_mfma_f32_16x16x32_bf16 v[18:21], v[158:161], v[204:207], v[18:21]
	v_mfma_f32_16x16x32_bf16 v[6:9], v[150:153], v[212:215], v[6:9]
	v_mfma_f32_16x16x32_bf16 v[2:5], v[158:161], v[212:215], v[2:5]
	s_setprio 0
	s_barrier
; #define PG8_STAGE(bufoff, gbase, voff) do { _Pragma("unroll") for (int _i = 0; _i < 2; ++_i) \
;         __builtin_amdgcn_global_load_lds((const unsigned*)((const char*)(gbase) + (voff)[_i]), (PG8_LAS unsigned*)(lds + (bufoff) + ldsw + _i * 8192), 16, 0, 0); } while (0)
; #define PG8_LDA(dst, b, h) do { _Pragma("unroll") for (int m = 0; m < 4; ++m) _Pragma("unroll") for (int k = 0; k < 2; ++k) dst[m][k] = *(const PG8_LAS bf16x8*)(lds + PG8_SA(b, h) + aoff + m * 2048 + k * 1024); } while (0)
; #define PG8_LDB(dst, b, h) do { _Pragma("unroll") for (int n = 0; n < 2; ++n) _Pragma("unroll") for (int k = 0; k < 2; ++k) dst[n][k] = *(const PG8_LAS bf16x8*)(lds + PG8_SB(b, h) + boff + n * 2048 + k * 1024); } while (0)
; #define PG8_MMA(ai, bj, At, Bt) do { __builtin_amdgcn_s_setprio(1); _Pragma("unroll") for (int m = 0; m < 4; ++m) _Pragma("unroll") for (int n = 0; n < 2; ++n) _Pragma("unroll") for (int k = 0; k < 2; ++k) \
;         acc[ai][bj][m][n] = __builtin_amdgcn_mfma_f32_16x16x32_bf16(Bt[n][k], At[m][k], acc[ai][bj][m][n], 0, 0, 0); __builtin_amdgcn_s_setprio(0); } while (0)
; #define PG8_WAIT_V(n) asm volatile("s_waitcnt vmcnt(" #n ")" ::: "memory")
; #define PG8_WAIT_L(n) asm volatile("s_waitcnt lgkmcnt(" #n ")" ::: "memory")
; #define PG8_BAR __builtin_amdgcn_s_barrier()
; #define PG8_SCHED __builtin_amdgcn_sched_barrier(0)
; template <class Epi, class Sched, bool ALIGN_EPI = false, bool SP2 = false>
; __device__ __forceinline__ void gemm_phase(PG8_LAS unsigned char* lds, const Gemm g, const Sched& S, const Epi& E) {
;     ...
;             PG8_LDB(B0, 1, 0); PG8_LDB(B1, 1, 1); PG8_SCHED; PG8_LDA(At, 1, 0); PG8_STAGE(PG8_SA(0, 1), a2 + hstep, voffA);
;             PG8_WAIT_V(8); PG8_WAIT_L(0); PG8_BAR; PG8_MMA(0, 0, At, B0); PG8_MMA(0, 1, At, B1); PG8_BAR; PG8_SCHED;
	s_add_i32 s43, 0, 0x18000
	s_add_i32 s46, 0, 0x1c000
	v_add_u32_e32 v142, s43, v217
	v_add_u32_e32 v158, s46, v217
	ds_read_b128 v[130:133], v142
	ds_read_b128 v[134:137], v142 offset:1024
	ds_read_b128 v[138:141], v142 offset:2048
	ds_read_b128 v[142:145], v142 offset:3072
	ds_read_b128 v[146:149], v158
	ds_read_b128 v[150:153], v158 offset:1024
	ds_read_b128 v[154:157], v158 offset:2048
	ds_read_b128 v[158:161], v158 offset:3072
	s_add_u32 s44, s44, 0x40000
	s_addc_u32 s45, s45, 0
	s_mov_b32 m0, s53
	v_lshl_add_u64 v[234:235], s[44:45], 0, v[176:177]
	ds_read_b128 v[162:165], v220 offset:32768
	ds_read_b128 v[166:169], v220 offset:33792
	ds_read_b128 v[170:173], v220 offset:34816
	ds_read_b128 v[196:199], v220 offset:35840
	ds_read_b128 v[200:203], v220 offset:36864
	ds_read_b128 v[204:207], v220 offset:37888
	ds_read_b128 v[208:211], v220 offset:38912
	ds_read_b128 v[212:215], v220 offset:39936
	global_load_lds_dwordx4 v[234:235], off
	v_lshl_add_u64 v[234:235], s[44:45], 0, v[180:181]
	s_mov_b32 m0, s54
	s_nop 0
	global_load_lds_dwordx4 v[234:235], off
	s_waitcnt vmcnt(8)
	s_waitcnt lgkmcnt(0)
	s_barrier
	s_setprio 1
	s_waitcnt lgkmcnt(0)
	v_mfma_f32_16x16x32_bf16 v[126:129], v[130:133], v[162:165], v[126:129]
	v_mfma_f32_16x16x32_bf16 v[122:125], v[138:141], v[162:165], v[122:125]
	v_mfma_f32_16x16x32_bf16 v[110:113], v[130:133], v[170:173], v[110:113]
	v_mfma_f32_16x16x32_bf16 v[106:109], v[138:141], v[170:173], v[106:109]
	v_mfma_f32_16x16x32_bf16 v[94:97], v[130:133], v[200:203], v[94:97]
	v_mfma_f32_16x16x32_bf16 v[90:93], v[138:141], v[200:203], v[90:93]
	v_mfma_f32_16x16x32_bf16 v[78:81], v[130:133], v[208:211], v[78:81]
	v_mfma_f32_16x16x32_bf16 v[74:77], v[138:141], v[208:211], v[74:77]
	v_mfma_f32_16x16x32_bf16 v[126:129], v[134:137], v[166:169], v[126:129]
	v_mfma_f32_16x16x32_bf16 v[122:125], v[142:145], v[166:169], v[122:125]
	v_mfma_f32_16x16x32_bf16 v[110:113], v[134:137], v[196:199], v[110:113]
	v_mfma_f32_16x16x32_bf16 v[106:109], v[142:145], v[196:199], v[106:109]
	v_mfma_f32_16x16x32_bf16 v[94:97], v[134:137], v[204:207], v[94:97]
	v_mfma_f32_16x16x32_bf16 v[90:93], v[142:145], v[204:207], v[90:93]
	v_mfma_f32_16x16x32_bf16 v[78:81], v[134:137], v[212:215], v[78:81]
	v_mfma_f32_16x16x32_bf16 v[74:77], v[142:145], v[212:215], v[74:77]
	s_setprio 0
	s_setprio 1
	v_mfma_f32_16x16x32_bf16 v[118:121], v[146:149], v[162:165], v[118:121]
	v_mfma_f32_16x16x32_bf16 v[114:117], v[154:157], v[162:165], v[114:117]
	v_mfma_f32_16x16x32_bf16 v[102:105], v[146:149], v[170:173], v[102:105]
	v_mfma_f32_16x16x32_bf16 v[98:101], v[154:157], v[170:173], v[98:101]
	v_mfma_f32_16x16x32_bf16 v[86:89], v[146:149], v[200:203], v[86:89]
	v_mfma_f32_16x16x32_bf16 v[82:85], v[154:157], v[200:203], v[82:85]
	v_mfma_f32_16x16x32_bf16 v[70:73], v[146:149], v[208:211], v[70:73]
	v_mfma_f32_16x16x32_bf16 v[66:69], v[154:157], v[208:211], v[66:69]
	v_mfma_f32_16x16x32_bf16 v[118:121], v[150:153], v[166:169], v[118:121]
	v_mfma_f32_16x16x32_bf16 v[114:117], v[158:161], v[166:169], v[114:117]
	v_mfma_f32_16x16x32_bf16 v[102:105], v[150:153], v[196:199], v[102:105]
	v_mfma_f32_16x16x32_bf16 v[98:101], v[158:161], v[196:199], v[98:101]
	v_mfma_f32_16x16x32_bf16 v[86:89], v[150:153], v[204:207], v[86:89]
	v_mfma_f32_16x16x32_bf16 v[82:85], v[158:161], v[204:207], v[82:85]
	v_mfma_f32_16x16x32_bf16 v[70:73], v[150:153], v[212:215], v[70:73]
	v_mfma_f32_16x16x32_bf16 v[66:69], v[158:161], v[212:215], v[66:69]
	s_setprio 0
	s_barrier
; #define PG8_STAGE(bufoff, gbase, voff) do { _Pragma("unroll") for (int _i = 0; _i < 2; ++_i) \
;         __builtin_amdgcn_global_load_lds((const unsigned*)((const char*)(gbase) + (voff)[_i]), (PG8_LAS unsigned*)(lds + (bufoff) + ldsw + _i * 8192), 16, 0, 0); } while (0)
; #define PG8_LDA(dst, b, h) do { _Pragma("unroll") for (int m = 0; m < 4; ++m) _Pragma("unroll") for (int k = 0; k < 2; ++k) dst[m][k] = *(const PG8_LAS bf16x8*)(lds + PG8_SA(b, h) + aoff + m * 2048 + k * 1024); } while (0)
; #define PG8_MMA(ai, bj, At, Bt) do { __builtin_amdgcn_s_setprio(1); _Pragma("unroll") for (int m = 0; m < 4; ++m) _Pragma("unroll") for (int n = 0; n < 2; ++n) _Pragma("unroll") for (int k = 0; k < 2; ++k) \
;         acc[ai][bj][m][n] = __builtin_amdgcn_mfma_f32_16x16x32_bf16(Bt[n][k], At[m][k], acc[ai][bj][m][n], 0, 0, 0); __builtin_amdgcn_s_setprio(0); } while (0)
; #define PG8_WAIT_V(n) asm volatile("s_waitcnt vmcnt(" #n ")" ::: "memory")
; #define PG8_WAIT_L(n) asm volatile("s_waitcnt lgkmcnt(" #n ")" ::: "memory")
; #define PG8_BAR __builtin_amdgcn_s_barrier()
; #define PG8_SCHED __builtin_amdgcn_sched_barrier(0)
; template <class Epi, class Sched, bool ALIGN_EPI = false, bool SP2 = false>
; __device__ __forceinline__ void gemm_phase(PG8_LAS unsigned char* lds, const Gemm g, const Sched& S, const Epi& E) {
;     ...
;         for (int t = 0; t < nt; t += 2) {
;             const bool last = (t == nt - 2);
;             const char* a1 = cA + (size_t)(t + 1) * kstep;
;             const char* a2 = last ? nA : cA + (size_t)(t + 2) * kstep; const char* b2 = last ? nB : cB + (size_t)(t + 2) * kstep;
;     ...
;             PG8_LDA(At, 1, 1); PG8_STAGE(PG8_SB(1, 0), b3, voffB); PG8_STAGE(PG8_SB(1, 1), b3 + hstep, voffB); PG8_STAGE(PG8_SA(1, 0), a3, voffA);
;             PG8_WAIT_V(8); PG8_WAIT_L(0); PG8_BAR; PG8_MMA(1, 0, At, B0); PG8_MMA(1, 1, At, B1); PG8_BAR; PG8_SCHED;
	s_add_i32 s43, s43, s50
	v_lshl_add_u64 v[226:227], v[226:227], 0, s[20:21]
	s_mov_b32 m0, s43
	ds_read_b128 v[162:165], v220 offset:49152
	ds_read_b128 v[166:169], v220 offset:50176
	ds_read_b128 v[170:173], v220 offset:51200
	ds_read_b128 v[196:199], v220 offset:52224
	ds_read_b128 v[200:203], v220 offset:53248
	ds_read_b128 v[204:207], v220 offset:54272
	ds_read_b128 v[208:211], v220 offset:55296
	ds_read_b128 v[212:215], v220 offset:56320
	global_load_lds_dwordx4 v[226:227], off
	s_add_i32 m0, s43, 0x2000
	s_add_u32 s6, s6, 0x40080
	v_lshl_add_u64 v[226:227], v[228:229], 0, s[20:21]
	s_addc_u32 s7, s7, 0
	s_add_i32 s43, s46, s50
	global_load_lds_dwordx4 v[226:227], off
	s_waitcnt vmcnt(4)
	s_waitcnt lgkmcnt(0)
	s_barrier
	s_setprio 1
	s_waitcnt lgkmcnt(0)
	v_mfma_f32_16x16x32_bf16 v[62:65], v[130:133], v[162:165], v[62:65]
	v_mfma_f32_16x16x32_bf16 v[58:61], v[138:141], v[162:165], v[58:61]
	v_mfma_f32_16x16x32_bf16 v[46:49], v[130:133], v[170:173], v[46:49]
	v_mfma_f32_16x16x32_bf16 v[42:45], v[138:141], v[170:173], v[42:45]
	v_lshl_add_u64 v[226:227], s[6:7], 0, v[178:179]
	s_mov_b32 m0, s43
	s_nop 0
	global_load_lds_dwordx4 v[226:227], off
	v_mfma_f32_16x16x32_bf16 v[30:33], v[130:133], v[200:203], v[30:33]
	v_mfma_f32_16x16x32_bf16 v[26:29], v[138:141], v[200:203], v[26:29]
	v_mfma_f32_16x16x32_bf16 v[14:17], v[130:133], v[208:211], v[14:17]
	v_mfma_f32_16x16x32_bf16 v[10:13], v[138:141], v[208:211], v[10:13]
	v_mfma_f32_16x16x32_bf16 v[62:65], v[134:137], v[166:169], v[62:65]
	v_mfma_f32_16x16x32_bf16 v[58:61], v[142:145], v[166:169], v[58:61]
	v_mfma_f32_16x16x32_bf16 v[46:49], v[134:137], v[196:199], v[46:49]
	v_mfma_f32_16x16x32_bf16 v[42:45], v[142:145], v[196:199], v[42:45]
	v_lshl_add_u64 v[226:227], s[6:7], 0, v[182:183]
	s_add_i32 m0, s43, 0x2000
	s_nop 0
	global_load_lds_dwordx4 v[226:227], off
	v_mfma_f32_16x16x32_bf16 v[30:33], v[134:137], v[204:207], v[30:33]
	v_mfma_f32_16x16x32_bf16 v[26:29], v[142:145], v[204:207], v[26:29]
	v_mfma_f32_16x16x32_bf16 v[14:17], v[134:137], v[212:215], v[14:17]
	v_mfma_f32_16x16x32_bf16 v[10:13], v[142:145], v[212:215], v[10:13]
	s_setprio 0
	s_setprio 1
	v_mfma_f32_16x16x32_bf16 v[54:57], v[146:149], v[162:165], v[54:57]
	v_mfma_f32_16x16x32_bf16 v[50:53], v[154:157], v[162:165], v[50:53]
	v_mfma_f32_16x16x32_bf16 v[38:41], v[146:149], v[170:173], v[38:41]
	v_mfma_f32_16x16x32_bf16 v[34:37], v[154:157], v[170:173], v[34:37]
	v_lshl_add_u64 v[226:227], v[230:231], 0, s[20:21]
	s_mov_b32 m0, s67
	s_nop 0
	global_load_lds_dwordx4 v[226:227], off
	v_mfma_f32_16x16x32_bf16 v[22:25], v[146:149], v[200:203], v[22:25]
	v_mfma_f32_16x16x32_bf16 v[18:21], v[154:157], v[200:203], v[18:21]
	v_mfma_f32_16x16x32_bf16 v[6:9], v[146:149], v[208:211], v[6:9]
	v_mfma_f32_16x16x32_bf16 v[2:5], v[154:157], v[208:211], v[2:5]
	v_mfma_f32_16x16x32_bf16 v[54:57], v[150:153], v[166:169], v[54:57]
	v_mfma_f32_16x16x32_bf16 v[50:53], v[158:161], v[166:169], v[50:53]
	v_mfma_f32_16x16x32_bf16 v[38:41], v[150:153], v[196:199], v[38:41]
	v_mfma_f32_16x16x32_bf16 v[34:37], v[158:161], v[196:199], v[34:37]
	v_lshl_add_u64 v[226:227], v[232:233], 0, s[20:21]
	s_mov_b32 m0, s68
	s_nop 0
	global_load_lds_dwordx4 v[226:227], off
	v_mfma_f32_16x16x32_bf16 v[22:25], v[150:153], v[204:207], v[22:25]
	v_mfma_f32_16x16x32_bf16 v[18:21], v[158:161], v[204:207], v[18:21]
	v_mfma_f32_16x16x32_bf16 v[6:9], v[150:153], v[212:215], v[6:9]
	v_mfma_f32_16x16x32_bf16 v[2:5], v[158:161], v[212:215], v[2:5]
	s_setprio 0
	s_barrier
	s_add_i32 s37, s37, 2
	s_add_u32 s4, s4, 0x100
	s_addc_u32 s5, s5, 0
	s_add_u32 s33, s33, 0x100
	s_addc_u32 s35, s35, 0
	s_cmp_gt_u32 s37, 13
	s_cbranch_scc0 .LBB0_411
	s_and_b64 vcc, exec, s[22:23]
	s_cbranch_vccz .LBB0_414
	s_barrier
